# spatial gating units: LayerNorm row statistics via DPP row rotations and broadcasts instead of serialized LDS bpermutes
# speedup vs baseline: 1.0034x; 1.0034x over previous
.LBB0_295:
	v_readfirstlane_b32 vcc_lo, v73
	s_nop 1
	v_mov_b32_e32 v222, vcc_lo
	v_add_co_u32_e32 v0, vcc, 0xffff9000, v64
	s_movk_i32 s0, 0xc000
	s_nop 0
	v_addc_co_u32_e32 v1, vcc, -1, v65, vcc
	global_load_dwordx4 v[60:63], v[0:1], off offset:-1024
	global_load_dwordx4 v[56:59], v[0:1], off
	v_add_co_u32_e32 v0, vcc, 0xffffa000, v64
	s_waitcnt vmcnt(0)
	v_and_b32_e32 v75, 0xffff0000, v60
	v_addc_co_u32_e32 v1, vcc, -1, v65, vcc
	global_load_dwordx4 v[52:55], v[0:1], off offset:-1024
	global_load_dwordx4 v[48:51], v[0:1], off
	v_add_co_u32_e32 v0, vcc, 0xffffb000, v64
	v_and_b32_e32 v77, 0xffff0000, v61
	s_nop 0
	v_addc_co_u32_e32 v1, vcc, -1, v65, vcc
	global_load_dwordx4 v[44:47], v[0:1], off offset:-1024
	global_load_dwordx4 v[40:43], v[0:1], off
	v_add_co_u32_e32 v0, vcc, s0, v64
	v_lshlrev_b32_e32 v61, 16, v61
	s_nop 0
	v_addc_co_u32_e32 v1, vcc, -1, v65, vcc
	global_load_dwordx4 v[36:39], v[0:1], off offset:-1024
	v_add_co_u32_e32 v0, vcc, s53, v64
	v_lshlrev_b32_e32 v60, 16, v60
	s_nop 0
	v_addc_co_u32_e32 v1, vcc, -1, v65, vcc
	global_load_dwordx4 v[32:35], v[0:1], off offset:-4096
	global_load_dwordx4 v[28:31], v[0:1], off offset:-1024
	global_load_dwordx4 v[24:27], v[0:1], off
	v_add_co_u32_e32 v0, vcc, s14, v64
	v_lshlrev_b32_e32 v79, 16, v62
	s_nop 0
	v_addc_co_u32_e32 v1, vcc, -1, v65, vcc
	global_load_dwordx4 v[20:23], v[0:1], off offset:-1024
	global_load_dwordx4 v[16:19], v[0:1], off
	v_add_co_u32_e32 v0, vcc, s15, v64
	v_and_b32_e32 v81, 0xffff0000, v62
	s_nop 0
	v_addc_co_u32_e32 v1, vcc, -1, v65, vcc
	global_load_dwordx4 v[12:15], v[0:1], off offset:-1024
	global_load_dwordx4 v[4:7], v[64:65], off offset:-4096
	global_load_dwordx4 v[8:11], v[64:65], off offset:-1024
	s_waitcnt lgkmcnt(0)
	global_load_dwordx4 v[0:3], v[64:65], off
	v_mul_f32_e32 v86, v60, v60
	v_mov_b32_e32 v62, v61
	v_mov_b32_e32 v87, v61
	v_mul_f32_e32 v76, v75, v75
	v_mul_f32_e32 v136, v77, v77
	v_pk_add_f32 v[76:77], v[86:87], v[76:77]
	v_pk_mul_f32 v[86:87], v[60:61], v[62:63] op_sel:[1,0] op_sel_hi:[0,1]
	v_pk_add_f32 v[60:61], v[60:61], v[74:75] op_sel:[1,0] op_sel_hi:[0,1]
	v_mov_b32_e32 v87, v61
	v_mul_f32_e32 v78, v79, v79
	v_mul_f32_e32 v80, v81, v81
	v_pk_add_f32 v[60:61], v[86:87], v[136:137]
	v_pk_add_f32 v[74:75], v[78:79], v[80:81]
	v_pk_add_f32 v[60:61], v[76:77], v[60:61]
	v_and_b32_e32 v77, 0xffff0000, v56
	v_pk_add_f32 v[60:61], v[74:75], v[60:61]
	v_lshlrev_b32_e32 v75, 16, v63
	v_and_b32_e32 v63, 0xffff0000, v63
	v_mul_f32_e32 v74, v75, v75
	v_mul_f32_e32 v62, v63, v63
	v_pk_add_f32 v[62:63], v[74:75], v[62:63]
	v_lshlrev_b32_e32 v75, 16, v56
	v_mul_f32_e32 v74, v75, v75
	v_mul_f32_e32 v76, v77, v77
	v_lshlrev_b32_e32 v79, 16, v57
	v_and_b32_e32 v57, 0xffff0000, v57
	v_mul_f32_e32 v78, v79, v79
	v_mul_f32_e32 v56, v57, v57
	v_lshlrev_b32_e32 v81, 16, v58
	v_and_b32_e32 v87, 0xffff0000, v58
	v_pk_add_f32 v[60:61], v[62:63], v[60:61]
	v_pk_add_f32 v[62:63], v[74:75], v[76:77]
	v_mul_f32_e32 v80, v81, v81
	v_mul_f32_e32 v86, v87, v87
	v_lshlrev_b32_e32 v89, 16, v59
	v_and_b32_e32 v59, 0xffff0000, v59
	v_pk_add_f32 v[60:61], v[62:63], v[60:61]
	v_pk_add_f32 v[56:57], v[78:79], v[56:57]
	v_mul_f32_e32 v88, v89, v89
	v_mul_f32_e32 v58, v59, v59
	v_pk_add_f32 v[56:57], v[56:57], v[60:61]
	v_pk_add_f32 v[60:61], v[80:81], v[86:87]
	v_pk_add_f32 v[58:59], v[88:89], v[58:59]
	v_pk_add_f32 v[56:57], v[60:61], v[56:57]
	s_nop 0
	v_pk_add_f32 v[56:57], v[58:59], v[56:57]
	s_nop 1
	v_add_f32_dpp v56, v56, v56 row_ror:8 row_mask:0xf bank_mask:0xf
	v_add_f32_dpp v57, v57, v57 row_ror:8 row_mask:0xf bank_mask:0xf
	s_nop 0
	v_add_f32_dpp v56, v56, v56 row_ror:4 row_mask:0xf bank_mask:0xf
	v_add_f32_dpp v57, v57, v57 row_ror:4 row_mask:0xf bank_mask:0xf
	s_nop 0
	v_add_f32_dpp v56, v56, v56 row_ror:2 row_mask:0xf bank_mask:0xf
	v_add_f32_dpp v57, v57, v57 row_ror:2 row_mask:0xf bank_mask:0xf
	s_nop 0
	v_add_f32_dpp v56, v56, v56 row_ror:1 row_mask:0xf bank_mask:0xf
	v_add_f32_dpp v57, v57, v57 row_ror:1 row_mask:0xf bank_mask:0xf
	s_nop 0
	v_add_f32_dpp v56, v56, v56 row_bcast:15 row_mask:0xa bank_mask:0xf
	v_add_f32_dpp v57, v57, v57 row_bcast:15 row_mask:0xa bank_mask:0xf
	s_nop 0
	v_add_f32_dpp v56, v56, v56 row_bcast:31 row_mask:0xc bank_mask:0xf
	v_add_f32_dpp v57, v57, v57 row_bcast:31 row_mask:0xc bank_mask:0xf
	s_nop 0
	s_mov_b64 s[0:1], exec
	s_mov_b32 exec_lo, 0
	s_mov_b32 exec_hi, 0x80000000
	s_nop 0
	v_pk_mul_f32 v[56:57], v[56:57], s[20:21] op_sel_hi:[1,0]
	s_nop 0
	v_fma_f32 v56, -v57, v57, v56
	v_max_f32_e32 v56, 0, v56
	v_add_f32_e32 v56, 0x358637bd, v56
	v_mul_f32_e32 v58, 0x4b800000, v56
	v_cmp_gt_f32_e32 vcc, s36, v56
	s_nop 1
	v_cndmask_b32_e32 v56, v56, v58, vcc
	v_rsq_f32_e32 v56, v56
	s_nop 0
	v_mul_f32_e32 v58, 0x45800000, v56
	v_cndmask_b32_e32 v59, v56, v58, vcc
	v_mov_b32_e32 v58, v57
	ds_write_b64 v222, v[58:59]
.LBB0_297:
	s_or_b64 exec, exec, s[0:1]
	s_waitcnt vmcnt(13)
	v_and_b32_e32 v57, 0xffff0000, v52
	s_waitcnt lgkmcnt(1)
	v_and_b32_e32 v59, 0xffff0000, v53
	v_lshlrev_b32_e32 v53, 16, v53
	v_lshlrev_b32_e32 v52, 16, v52
	v_lshlrev_b32_e32 v61, 16, v54
	v_and_b32_e32 v63, 0xffff0000, v54
	v_mul_f32_e32 v74, v52, v52
	v_mov_b32_e32 v54, v53
	v_mov_b32_e32 v75, v53
	s_waitcnt lgkmcnt(0)
	v_mul_f32_e32 v58, v57, v57
	v_mul_f32_e32 v136, v59, v59
	v_pk_add_f32 v[58:59], v[74:75], v[58:59]
	v_pk_mul_f32 v[74:75], v[52:53], v[54:55] op_sel:[1,0] op_sel_hi:[0,1]
	v_pk_add_f32 v[52:53], v[52:53], v[56:57] op_sel:[1,0] op_sel_hi:[0,1]
	v_mov_b32_e32 v75, v53
	v_mul_f32_e32 v60, v61, v61
	v_mul_f32_e32 v62, v63, v63
	v_pk_add_f32 v[52:53], v[74:75], v[136:137]
	v_pk_add_f32 v[56:57], v[60:61], v[62:63]
	v_pk_add_f32 v[52:53], v[58:59], v[52:53]
	s_waitcnt vmcnt(12)
	v_and_b32_e32 v59, 0xffff0000, v48
	v_pk_add_f32 v[52:53], v[56:57], v[52:53]
	v_lshlrev_b32_e32 v57, 16, v55
	v_and_b32_e32 v55, 0xffff0000, v55
	v_mul_f32_e32 v56, v57, v57
	v_mul_f32_e32 v54, v55, v55
	v_pk_add_f32 v[54:55], v[56:57], v[54:55]
	v_lshlrev_b32_e32 v57, 16, v48
	v_mul_f32_e32 v56, v57, v57
	v_mul_f32_e32 v58, v59, v59
	v_lshlrev_b32_e32 v61, 16, v49
	v_and_b32_e32 v49, 0xffff0000, v49
	v_mul_f32_e32 v60, v61, v61
	v_mul_f32_e32 v48, v49, v49
	v_lshlrev_b32_e32 v63, 16, v50
	v_and_b32_e32 v75, 0xffff0000, v50
	v_pk_add_f32 v[52:53], v[54:55], v[52:53]
	v_pk_add_f32 v[54:55], v[56:57], v[58:59]
	v_mul_f32_e32 v62, v63, v63
	v_mul_f32_e32 v74, v75, v75
	v_lshlrev_b32_e32 v77, 16, v51
	v_and_b32_e32 v51, 0xffff0000, v51
	v_pk_add_f32 v[52:53], v[54:55], v[52:53]
	v_pk_add_f32 v[48:49], v[60:61], v[48:49]
	v_mul_f32_e32 v76, v77, v77
	v_mul_f32_e32 v50, v51, v51
	v_pk_add_f32 v[48:49], v[48:49], v[52:53]
	v_pk_add_f32 v[52:53], v[62:63], v[74:75]
	v_pk_add_f32 v[50:51], v[76:77], v[50:51]
	v_pk_add_f32 v[48:49], v[52:53], v[48:49]
	s_nop 0
	v_pk_add_f32 v[48:49], v[50:51], v[48:49]
	s_nop 1
	v_add_f32_dpp v48, v48, v48 row_ror:8 row_mask:0xf bank_mask:0xf
	v_add_f32_dpp v49, v49, v49 row_ror:8 row_mask:0xf bank_mask:0xf
	s_nop 0
	v_add_f32_dpp v48, v48, v48 row_ror:4 row_mask:0xf bank_mask:0xf
	v_add_f32_dpp v49, v49, v49 row_ror:4 row_mask:0xf bank_mask:0xf
	s_nop 0
	v_add_f32_dpp v48, v48, v48 row_ror:2 row_mask:0xf bank_mask:0xf
	v_add_f32_dpp v49, v49, v49 row_ror:2 row_mask:0xf bank_mask:0xf
	s_nop 0
	v_add_f32_dpp v48, v48, v48 row_ror:1 row_mask:0xf bank_mask:0xf
	v_add_f32_dpp v49, v49, v49 row_ror:1 row_mask:0xf bank_mask:0xf
	s_nop 0
	v_add_f32_dpp v48, v48, v48 row_bcast:15 row_mask:0xa bank_mask:0xf
	v_add_f32_dpp v49, v49, v49 row_bcast:15 row_mask:0xa bank_mask:0xf
	s_nop 0
	v_add_f32_dpp v48, v48, v48 row_bcast:31 row_mask:0xc bank_mask:0xf
	v_add_f32_dpp v49, v49, v49 row_bcast:31 row_mask:0xc bank_mask:0xf
	s_nop 0
	s_mov_b64 s[0:1], exec
	s_mov_b32 exec_lo, 0
	s_mov_b32 exec_hi, 0x80000000
	s_nop 0
	v_pk_mul_f32 v[48:49], v[48:49], s[20:21] op_sel_hi:[1,0]
	s_nop 0
	v_fma_f32 v48, -v49, v49, v48
	v_max_f32_e32 v48, 0, v48
	v_add_f32_e32 v48, 0x358637bd, v48
	v_mul_f32_e32 v50, 0x4b800000, v48
	v_cmp_gt_f32_e32 vcc, s36, v48
	s_nop 1
	v_cndmask_b32_e32 v48, v48, v50, vcc
	v_rsq_f32_e32 v48, v48
	s_nop 0
	v_mul_f32_e32 v50, 0x45800000, v48
	v_cndmask_b32_e32 v51, v48, v50, vcc
	v_mov_b32_e32 v50, v49
	ds_write_b64 v222, v[50:51] offset:8
.LBB0_299:
	s_or_b64 exec, exec, s[0:1]
	s_waitcnt vmcnt(11)
	v_and_b32_e32 v49, 0xffff0000, v44
	s_waitcnt lgkmcnt(1)
	v_and_b32_e32 v51, 0xffff0000, v45
	v_lshlrev_b32_e32 v45, 16, v45
	v_lshlrev_b32_e32 v44, 16, v44
	v_lshlrev_b32_e32 v53, 16, v46
	v_and_b32_e32 v55, 0xffff0000, v46
	v_mul_f32_e32 v56, v44, v44
	v_mov_b32_e32 v46, v45
	v_mov_b32_e32 v57, v45
	s_waitcnt lgkmcnt(0)
	v_mul_f32_e32 v50, v49, v49
	v_mul_f32_e32 v136, v51, v51
	v_pk_add_f32 v[50:51], v[56:57], v[50:51]
	v_pk_mul_f32 v[56:57], v[44:45], v[46:47] op_sel:[1,0] op_sel_hi:[0,1]
	v_pk_add_f32 v[44:45], v[44:45], v[48:49] op_sel:[1,0] op_sel_hi:[0,1]
	v_mov_b32_e32 v57, v45
	v_mul_f32_e32 v52, v53, v53
	v_mul_f32_e32 v54, v55, v55
	v_pk_add_f32 v[44:45], v[56:57], v[136:137]
	v_pk_add_f32 v[48:49], v[52:53], v[54:55]
	v_pk_add_f32 v[44:45], v[50:51], v[44:45]
	s_waitcnt vmcnt(10)
	v_and_b32_e32 v51, 0xffff0000, v40
	v_pk_add_f32 v[44:45], v[48:49], v[44:45]
	v_lshlrev_b32_e32 v49, 16, v47
	v_and_b32_e32 v47, 0xffff0000, v47
	v_mul_f32_e32 v48, v49, v49
	v_mul_f32_e32 v46, v47, v47
	v_pk_add_f32 v[46:47], v[48:49], v[46:47]
	v_lshlrev_b32_e32 v49, 16, v40
	v_mul_f32_e32 v48, v49, v49
	v_mul_f32_e32 v50, v51, v51
	v_lshlrev_b32_e32 v53, 16, v41
	v_and_b32_e32 v41, 0xffff0000, v41
	v_mul_f32_e32 v52, v53, v53
	v_mul_f32_e32 v40, v41, v41
	v_lshlrev_b32_e32 v55, 16, v42
	v_and_b32_e32 v57, 0xffff0000, v42
	v_pk_add_f32 v[44:45], v[46:47], v[44:45]
	v_pk_add_f32 v[46:47], v[48:49], v[50:51]
	v_mul_f32_e32 v54, v55, v55
	v_mul_f32_e32 v56, v57, v57
	v_lshlrev_b32_e32 v59, 16, v43
	v_and_b32_e32 v43, 0xffff0000, v43
	v_pk_add_f32 v[44:45], v[46:47], v[44:45]
	v_pk_add_f32 v[40:41], v[52:53], v[40:41]
	v_mul_f32_e32 v58, v59, v59
	v_mul_f32_e32 v42, v43, v43
	v_pk_add_f32 v[40:41], v[40:41], v[44:45]
	v_pk_add_f32 v[44:45], v[54:55], v[56:57]
	v_pk_add_f32 v[42:43], v[58:59], v[42:43]
	v_pk_add_f32 v[40:41], v[44:45], v[40:41]
	s_nop 0
	v_pk_add_f32 v[40:41], v[42:43], v[40:41]
	s_nop 1
	v_add_f32_dpp v40, v40, v40 row_ror:8 row_mask:0xf bank_mask:0xf
	v_add_f32_dpp v41, v41, v41 row_ror:8 row_mask:0xf bank_mask:0xf
	s_nop 0
	v_add_f32_dpp v40, v40, v40 row_ror:4 row_mask:0xf bank_mask:0xf
	v_add_f32_dpp v41, v41, v41 row_ror:4 row_mask:0xf bank_mask:0xf
	s_nop 0
	v_add_f32_dpp v40, v40, v40 row_ror:2 row_mask:0xf bank_mask:0xf
	v_add_f32_dpp v41, v41, v41 row_ror:2 row_mask:0xf bank_mask:0xf
	s_nop 0
	v_add_f32_dpp v40, v40, v40 row_ror:1 row_mask:0xf bank_mask:0xf
	v_add_f32_dpp v41, v41, v41 row_ror:1 row_mask:0xf bank_mask:0xf
	s_nop 0
	v_add_f32_dpp v40, v40, v40 row_bcast:15 row_mask:0xa bank_mask:0xf
	v_add_f32_dpp v41, v41, v41 row_bcast:15 row_mask:0xa bank_mask:0xf
	s_nop 0
	v_add_f32_dpp v40, v40, v40 row_bcast:31 row_mask:0xc bank_mask:0xf
	v_add_f32_dpp v41, v41, v41 row_bcast:31 row_mask:0xc bank_mask:0xf
	s_nop 0
	s_mov_b64 s[0:1], exec
	s_mov_b32 exec_lo, 0
	s_mov_b32 exec_hi, 0x80000000
	s_nop 0
	v_pk_mul_f32 v[40:41], v[40:41], s[20:21] op_sel_hi:[1,0]
	s_nop 0
	v_fma_f32 v40, -v41, v41, v40
	v_max_f32_e32 v40, 0, v40
	v_add_f32_e32 v40, 0x358637bd, v40
	v_mul_f32_e32 v42, 0x4b800000, v40
	v_cmp_gt_f32_e32 vcc, s36, v40
	s_nop 1
	v_cndmask_b32_e32 v40, v40, v42, vcc
	v_rsq_f32_e32 v40, v40
	s_nop 0
	v_mul_f32_e32 v42, 0x45800000, v40
	v_cndmask_b32_e32 v43, v40, v42, vcc
	v_mov_b32_e32 v42, v41
	ds_write_b64 v222, v[42:43] offset:16
.LBB0_301:
	s_or_b64 exec, exec, s[0:1]
	s_waitcnt vmcnt(9)
	v_and_b32_e32 v41, 0xffff0000, v36
	s_waitcnt lgkmcnt(1)
	v_and_b32_e32 v43, 0xffff0000, v37
	v_lshlrev_b32_e32 v37, 16, v37
	v_lshlrev_b32_e32 v36, 16, v36
	v_lshlrev_b32_e32 v45, 16, v38
	v_and_b32_e32 v47, 0xffff0000, v38
	v_mul_f32_e32 v48, v36, v36
	v_mov_b32_e32 v38, v37
	v_mov_b32_e32 v49, v37
	s_waitcnt lgkmcnt(0)
	v_mul_f32_e32 v42, v41, v41
	v_mul_f32_e32 v136, v43, v43
	v_pk_add_f32 v[42:43], v[48:49], v[42:43]
	v_pk_mul_f32 v[48:49], v[36:37], v[38:39] op_sel:[1,0] op_sel_hi:[0,1]
	v_pk_add_f32 v[36:37], v[36:37], v[40:41] op_sel:[1,0] op_sel_hi:[0,1]
	v_mov_b32_e32 v49, v37
	v_mul_f32_e32 v44, v45, v45
	v_mul_f32_e32 v46, v47, v47
	v_pk_add_f32 v[36:37], v[48:49], v[136:137]
	v_pk_add_f32 v[40:41], v[44:45], v[46:47]
	v_pk_add_f32 v[36:37], v[42:43], v[36:37]
	s_waitcnt vmcnt(8)
	v_and_b32_e32 v43, 0xffff0000, v32
	v_pk_add_f32 v[36:37], v[40:41], v[36:37]
	v_lshlrev_b32_e32 v41, 16, v39
	v_and_b32_e32 v39, 0xffff0000, v39
	v_mul_f32_e32 v40, v41, v41
	v_mul_f32_e32 v38, v39, v39
	v_pk_add_f32 v[38:39], v[40:41], v[38:39]
	v_lshlrev_b32_e32 v41, 16, v32
	v_mul_f32_e32 v40, v41, v41
	v_mul_f32_e32 v42, v43, v43
	v_lshlrev_b32_e32 v45, 16, v33
	v_and_b32_e32 v33, 0xffff0000, v33
	v_mul_f32_e32 v44, v45, v45
	v_mul_f32_e32 v32, v33, v33
	v_lshlrev_b32_e32 v47, 16, v34
	v_and_b32_e32 v49, 0xffff0000, v34
	v_pk_add_f32 v[36:37], v[38:39], v[36:37]
	v_pk_add_f32 v[38:39], v[40:41], v[42:43]
	v_mul_f32_e32 v46, v47, v47
	v_mul_f32_e32 v48, v49, v49
	v_lshlrev_b32_e32 v51, 16, v35
	v_and_b32_e32 v35, 0xffff0000, v35
	v_pk_add_f32 v[36:37], v[38:39], v[36:37]
	v_pk_add_f32 v[32:33], v[44:45], v[32:33]
	v_mul_f32_e32 v50, v51, v51
	v_mul_f32_e32 v34, v35, v35
	v_pk_add_f32 v[32:33], v[32:33], v[36:37]
	v_pk_add_f32 v[36:37], v[46:47], v[48:49]
	v_pk_add_f32 v[34:35], v[50:51], v[34:35]
	v_pk_add_f32 v[32:33], v[36:37], v[32:33]
	s_nop 0
	v_pk_add_f32 v[32:33], v[34:35], v[32:33]
	s_nop 1
	v_add_f32_dpp v32, v32, v32 row_ror:8 row_mask:0xf bank_mask:0xf
	v_add_f32_dpp v33, v33, v33 row_ror:8 row_mask:0xf bank_mask:0xf
	s_nop 0
	v_add_f32_dpp v32, v32, v32 row_ror:4 row_mask:0xf bank_mask:0xf
	v_add_f32_dpp v33, v33, v33 row_ror:4 row_mask:0xf bank_mask:0xf
	s_nop 0
	v_add_f32_dpp v32, v32, v32 row_ror:2 row_mask:0xf bank_mask:0xf
	v_add_f32_dpp v33, v33, v33 row_ror:2 row_mask:0xf bank_mask:0xf
	s_nop 0
	v_add_f32_dpp v32, v32, v32 row_ror:1 row_mask:0xf bank_mask:0xf
	v_add_f32_dpp v33, v33, v33 row_ror:1 row_mask:0xf bank_mask:0xf
	s_nop 0
	v_add_f32_dpp v32, v32, v32 row_bcast:15 row_mask:0xa bank_mask:0xf
	v_add_f32_dpp v33, v33, v33 row_bcast:15 row_mask:0xa bank_mask:0xf
	s_nop 0
	v_add_f32_dpp v32, v32, v32 row_bcast:31 row_mask:0xc bank_mask:0xf
	v_add_f32_dpp v33, v33, v33 row_bcast:31 row_mask:0xc bank_mask:0xf
	s_nop 0
	s_mov_b64 s[0:1], exec
	s_mov_b32 exec_lo, 0
	s_mov_b32 exec_hi, 0x80000000
	s_nop 0
	v_pk_mul_f32 v[32:33], v[32:33], s[20:21] op_sel_hi:[1,0]
	s_nop 0
	v_fma_f32 v32, -v33, v33, v32
	v_max_f32_e32 v32, 0, v32
	v_add_f32_e32 v32, 0x358637bd, v32
	v_mul_f32_e32 v34, 0x4b800000, v32
	v_cmp_gt_f32_e32 vcc, s36, v32
	s_nop 1
	v_cndmask_b32_e32 v32, v32, v34, vcc
	v_rsq_f32_e32 v32, v32
	s_nop 0
	v_mul_f32_e32 v34, 0x45800000, v32
	v_cndmask_b32_e32 v35, v32, v34, vcc
	v_mov_b32_e32 v34, v33
	ds_write_b64 v222, v[34:35] offset:24
.LBB0_303:
	s_or_b64 exec, exec, s[0:1]
	s_waitcnt vmcnt(7)
	v_and_b32_e32 v33, 0xffff0000, v28
	s_waitcnt lgkmcnt(1)
	v_and_b32_e32 v35, 0xffff0000, v29
	v_lshlrev_b32_e32 v29, 16, v29
	v_lshlrev_b32_e32 v28, 16, v28
	v_lshlrev_b32_e32 v37, 16, v30
	v_and_b32_e32 v39, 0xffff0000, v30
	v_mul_f32_e32 v40, v28, v28
	v_mov_b32_e32 v30, v29
	v_mov_b32_e32 v41, v29
	s_waitcnt lgkmcnt(0)
	v_mul_f32_e32 v34, v33, v33
	v_mul_f32_e32 v136, v35, v35
	v_pk_add_f32 v[34:35], v[40:41], v[34:35]
	v_pk_mul_f32 v[40:41], v[28:29], v[30:31] op_sel:[1,0] op_sel_hi:[0,1]
	v_pk_add_f32 v[28:29], v[28:29], v[32:33] op_sel:[1,0] op_sel_hi:[0,1]
	v_mov_b32_e32 v41, v29
	v_mul_f32_e32 v36, v37, v37
	v_mul_f32_e32 v38, v39, v39
	v_pk_add_f32 v[28:29], v[40:41], v[136:137]
	v_pk_add_f32 v[32:33], v[36:37], v[38:39]
	v_pk_add_f32 v[28:29], v[34:35], v[28:29]
	s_waitcnt vmcnt(6)
	v_and_b32_e32 v35, 0xffff0000, v24
	v_pk_add_f32 v[28:29], v[32:33], v[28:29]
	v_lshlrev_b32_e32 v33, 16, v31
	v_and_b32_e32 v31, 0xffff0000, v31
	v_mul_f32_e32 v32, v33, v33
	v_mul_f32_e32 v30, v31, v31
	v_pk_add_f32 v[30:31], v[32:33], v[30:31]
	v_lshlrev_b32_e32 v33, 16, v24
	v_mul_f32_e32 v32, v33, v33
	v_mul_f32_e32 v34, v35, v35
	v_lshlrev_b32_e32 v37, 16, v25
	v_and_b32_e32 v25, 0xffff0000, v25
	v_mul_f32_e32 v36, v37, v37
	v_mul_f32_e32 v24, v25, v25
	v_lshlrev_b32_e32 v39, 16, v26
	v_and_b32_e32 v41, 0xffff0000, v26
	v_pk_add_f32 v[28:29], v[30:31], v[28:29]
	v_pk_add_f32 v[30:31], v[32:33], v[34:35]
	v_mul_f32_e32 v38, v39, v39
	v_mul_f32_e32 v40, v41, v41
	v_lshlrev_b32_e32 v43, 16, v27
	v_and_b32_e32 v27, 0xffff0000, v27
	v_pk_add_f32 v[28:29], v[30:31], v[28:29]
	v_pk_add_f32 v[24:25], v[36:37], v[24:25]
	v_mul_f32_e32 v42, v43, v43
	v_mul_f32_e32 v26, v27, v27
	v_pk_add_f32 v[24:25], v[24:25], v[28:29]
	v_pk_add_f32 v[28:29], v[38:39], v[40:41]
	v_pk_add_f32 v[26:27], v[42:43], v[26:27]
	v_pk_add_f32 v[24:25], v[28:29], v[24:25]
	s_nop 0
	v_pk_add_f32 v[24:25], v[26:27], v[24:25]
	s_nop 1
	v_add_f32_dpp v24, v24, v24 row_ror:8 row_mask:0xf bank_mask:0xf
	v_add_f32_dpp v25, v25, v25 row_ror:8 row_mask:0xf bank_mask:0xf
	s_nop 0
	v_add_f32_dpp v24, v24, v24 row_ror:4 row_mask:0xf bank_mask:0xf
	v_add_f32_dpp v25, v25, v25 row_ror:4 row_mask:0xf bank_mask:0xf
	s_nop 0
	v_add_f32_dpp v24, v24, v24 row_ror:2 row_mask:0xf bank_mask:0xf
	v_add_f32_dpp v25, v25, v25 row_ror:2 row_mask:0xf bank_mask:0xf
	s_nop 0
	v_add_f32_dpp v24, v24, v24 row_ror:1 row_mask:0xf bank_mask:0xf
	v_add_f32_dpp v25, v25, v25 row_ror:1 row_mask:0xf bank_mask:0xf
	s_nop 0
	v_add_f32_dpp v24, v24, v24 row_bcast:15 row_mask:0xa bank_mask:0xf
	v_add_f32_dpp v25, v25, v25 row_bcast:15 row_mask:0xa bank_mask:0xf
	s_nop 0
	v_add_f32_dpp v24, v24, v24 row_bcast:31 row_mask:0xc bank_mask:0xf
	v_add_f32_dpp v25, v25, v25 row_bcast:31 row_mask:0xc bank_mask:0xf
	s_nop 0
	s_mov_b64 s[0:1], exec
	s_mov_b32 exec_lo, 0
	s_mov_b32 exec_hi, 0x80000000
	s_nop 0
	v_pk_mul_f32 v[24:25], v[24:25], s[20:21] op_sel_hi:[1,0]
	s_nop 0
	v_fma_f32 v24, -v25, v25, v24
	v_max_f32_e32 v24, 0, v24
	v_add_f32_e32 v24, 0x358637bd, v24
	v_mul_f32_e32 v26, 0x4b800000, v24
	v_cmp_gt_f32_e32 vcc, s36, v24
	s_nop 1
	v_cndmask_b32_e32 v24, v24, v26, vcc
	v_rsq_f32_e32 v24, v24
	s_nop 0
	v_mul_f32_e32 v26, 0x45800000, v24
	v_cndmask_b32_e32 v27, v24, v26, vcc
	v_mov_b32_e32 v26, v25
	ds_write_b64 v222, v[26:27] offset:32
.LBB0_305:
	s_or_b64 exec, exec, s[0:1]
	s_waitcnt vmcnt(5)
	v_and_b32_e32 v25, 0xffff0000, v20
	s_waitcnt lgkmcnt(1)
	v_and_b32_e32 v27, 0xffff0000, v21
	v_lshlrev_b32_e32 v21, 16, v21
	v_lshlrev_b32_e32 v20, 16, v20
	v_lshlrev_b32_e32 v29, 16, v22
	v_and_b32_e32 v31, 0xffff0000, v22
	v_mul_f32_e32 v32, v20, v20
	v_mov_b32_e32 v22, v21
	v_mov_b32_e32 v33, v21
	s_waitcnt lgkmcnt(0)
	v_mul_f32_e32 v26, v25, v25
	v_mul_f32_e32 v136, v27, v27
	v_pk_add_f32 v[26:27], v[32:33], v[26:27]
	v_pk_mul_f32 v[32:33], v[20:21], v[22:23] op_sel:[1,0] op_sel_hi:[0,1]
	v_pk_add_f32 v[20:21], v[20:21], v[24:25] op_sel:[1,0] op_sel_hi:[0,1]
	v_mov_b32_e32 v33, v21
	v_mul_f32_e32 v28, v29, v29
	v_mul_f32_e32 v30, v31, v31
	v_pk_add_f32 v[20:21], v[32:33], v[136:137]
	v_pk_add_f32 v[24:25], v[28:29], v[30:31]
	v_pk_add_f32 v[20:21], v[26:27], v[20:21]
	s_waitcnt vmcnt(4)
	v_and_b32_e32 v27, 0xffff0000, v16
	v_pk_add_f32 v[20:21], v[24:25], v[20:21]
	v_lshlrev_b32_e32 v25, 16, v23
	v_and_b32_e32 v23, 0xffff0000, v23
	v_mul_f32_e32 v24, v25, v25
	v_mul_f32_e32 v22, v23, v23
	v_pk_add_f32 v[22:23], v[24:25], v[22:23]
	v_lshlrev_b32_e32 v25, 16, v16
	v_mul_f32_e32 v24, v25, v25
	v_mul_f32_e32 v26, v27, v27
	v_lshlrev_b32_e32 v29, 16, v17
	v_and_b32_e32 v17, 0xffff0000, v17
	v_mul_f32_e32 v28, v29, v29
	v_mul_f32_e32 v16, v17, v17
	v_lshlrev_b32_e32 v31, 16, v18
	v_and_b32_e32 v33, 0xffff0000, v18
	v_pk_add_f32 v[20:21], v[22:23], v[20:21]
	v_pk_add_f32 v[22:23], v[24:25], v[26:27]
	v_mul_f32_e32 v30, v31, v31
	v_mul_f32_e32 v32, v33, v33
	v_lshlrev_b32_e32 v35, 16, v19
	v_and_b32_e32 v19, 0xffff0000, v19
	v_pk_add_f32 v[20:21], v[22:23], v[20:21]
	v_pk_add_f32 v[16:17], v[28:29], v[16:17]
	v_mul_f32_e32 v34, v35, v35
	v_mul_f32_e32 v18, v19, v19
	v_pk_add_f32 v[16:17], v[16:17], v[20:21]
	v_pk_add_f32 v[20:21], v[30:31], v[32:33]
	v_pk_add_f32 v[18:19], v[34:35], v[18:19]
	v_pk_add_f32 v[16:17], v[20:21], v[16:17]
	s_nop 0
	v_pk_add_f32 v[16:17], v[18:19], v[16:17]
	s_nop 1
	v_add_f32_dpp v16, v16, v16 row_ror:8 row_mask:0xf bank_mask:0xf
	v_add_f32_dpp v17, v17, v17 row_ror:8 row_mask:0xf bank_mask:0xf
	s_nop 0
	v_add_f32_dpp v16, v16, v16 row_ror:4 row_mask:0xf bank_mask:0xf
	v_add_f32_dpp v17, v17, v17 row_ror:4 row_mask:0xf bank_mask:0xf
	s_nop 0
	v_add_f32_dpp v16, v16, v16 row_ror:2 row_mask:0xf bank_mask:0xf
	v_add_f32_dpp v17, v17, v17 row_ror:2 row_mask:0xf bank_mask:0xf
	s_nop 0
	v_add_f32_dpp v16, v16, v16 row_ror:1 row_mask:0xf bank_mask:0xf
	v_add_f32_dpp v17, v17, v17 row_ror:1 row_mask:0xf bank_mask:0xf
	s_nop 0
	v_add_f32_dpp v16, v16, v16 row_bcast:15 row_mask:0xa bank_mask:0xf
	v_add_f32_dpp v17, v17, v17 row_bcast:15 row_mask:0xa bank_mask:0xf
	s_nop 0
	v_add_f32_dpp v16, v16, v16 row_bcast:31 row_mask:0xc bank_mask:0xf
	v_add_f32_dpp v17, v17, v17 row_bcast:31 row_mask:0xc bank_mask:0xf
	s_nop 0
	s_mov_b64 s[0:1], exec
	s_mov_b32 exec_lo, 0
	s_mov_b32 exec_hi, 0x80000000
	s_nop 0
	v_pk_mul_f32 v[16:17], v[16:17], s[20:21] op_sel_hi:[1,0]
	s_nop 0
	v_fma_f32 v16, -v17, v17, v16
	v_max_f32_e32 v16, 0, v16
	v_add_f32_e32 v16, 0x358637bd, v16
	v_mul_f32_e32 v18, 0x4b800000, v16
	v_cmp_gt_f32_e32 vcc, s36, v16
	s_nop 1
	v_cndmask_b32_e32 v16, v16, v18, vcc
	v_rsq_f32_e32 v16, v16
	s_nop 0
	v_mul_f32_e32 v18, 0x45800000, v16
	v_cndmask_b32_e32 v19, v16, v18, vcc
	v_mov_b32_e32 v18, v17
	ds_write_b64 v222, v[18:19] offset:40
.LBB0_307:
	s_or_b64 exec, exec, s[0:1]
	s_waitcnt vmcnt(3)
	v_and_b32_e32 v17, 0xffff0000, v12
	s_waitcnt lgkmcnt(1)
	v_and_b32_e32 v19, 0xffff0000, v13
	v_lshlrev_b32_e32 v13, 16, v13
	v_lshlrev_b32_e32 v12, 16, v12
	v_lshlrev_b32_e32 v21, 16, v14
	v_and_b32_e32 v23, 0xffff0000, v14
	v_mul_f32_e32 v24, v12, v12
	v_mov_b32_e32 v14, v13
	v_mov_b32_e32 v25, v13
	s_waitcnt lgkmcnt(0)
	v_mul_f32_e32 v18, v17, v17
	v_mul_f32_e32 v136, v19, v19
	v_pk_add_f32 v[18:19], v[24:25], v[18:19]
	v_pk_mul_f32 v[24:25], v[12:13], v[14:15] op_sel:[1,0] op_sel_hi:[0,1]
	v_pk_add_f32 v[12:13], v[12:13], v[16:17] op_sel:[1,0] op_sel_hi:[0,1]
	v_mov_b32_e32 v25, v13
	v_mul_f32_e32 v20, v21, v21
	v_mul_f32_e32 v22, v23, v23
	v_pk_add_f32 v[12:13], v[24:25], v[136:137]
	v_pk_add_f32 v[16:17], v[20:21], v[22:23]
	v_pk_add_f32 v[12:13], v[18:19], v[12:13]
	s_waitcnt vmcnt(2)
	v_and_b32_e32 v19, 0xffff0000, v4
	v_pk_add_f32 v[12:13], v[16:17], v[12:13]
	v_lshlrev_b32_e32 v17, 16, v15
	v_and_b32_e32 v15, 0xffff0000, v15
	v_mul_f32_e32 v16, v17, v17
	v_mul_f32_e32 v14, v15, v15
	v_pk_add_f32 v[14:15], v[16:17], v[14:15]
	v_lshlrev_b32_e32 v17, 16, v4
	v_mul_f32_e32 v16, v17, v17
	v_mul_f32_e32 v18, v19, v19
	v_lshlrev_b32_e32 v21, 16, v5
	v_and_b32_e32 v5, 0xffff0000, v5
	v_mul_f32_e32 v20, v21, v21
	v_mul_f32_e32 v4, v5, v5
	v_lshlrev_b32_e32 v23, 16, v6
	v_and_b32_e32 v25, 0xffff0000, v6
	v_pk_add_f32 v[12:13], v[14:15], v[12:13]
	v_pk_add_f32 v[14:15], v[16:17], v[18:19]
	v_mul_f32_e32 v22, v23, v23
	v_mul_f32_e32 v24, v25, v25
	v_lshlrev_b32_e32 v27, 16, v7
	v_and_b32_e32 v7, 0xffff0000, v7
	v_pk_add_f32 v[12:13], v[14:15], v[12:13]
	v_pk_add_f32 v[4:5], v[20:21], v[4:5]
	v_mul_f32_e32 v26, v27, v27
	v_mul_f32_e32 v6, v7, v7
	v_pk_add_f32 v[4:5], v[4:5], v[12:13]
	v_pk_add_f32 v[12:13], v[22:23], v[24:25]
	v_pk_add_f32 v[6:7], v[26:27], v[6:7]
	v_pk_add_f32 v[4:5], v[12:13], v[4:5]
	s_nop 0
	v_pk_add_f32 v[4:5], v[6:7], v[4:5]
	s_nop 1
	v_add_f32_dpp v4, v4, v4 row_ror:8 row_mask:0xf bank_mask:0xf
	v_add_f32_dpp v5, v5, v5 row_ror:8 row_mask:0xf bank_mask:0xf
	s_nop 0
	v_add_f32_dpp v4, v4, v4 row_ror:4 row_mask:0xf bank_mask:0xf
	v_add_f32_dpp v5, v5, v5 row_ror:4 row_mask:0xf bank_mask:0xf
	s_nop 0
	v_add_f32_dpp v4, v4, v4 row_ror:2 row_mask:0xf bank_mask:0xf
	v_add_f32_dpp v5, v5, v5 row_ror:2 row_mask:0xf bank_mask:0xf
	s_nop 0
	v_add_f32_dpp v4, v4, v4 row_ror:1 row_mask:0xf bank_mask:0xf
	v_add_f32_dpp v5, v5, v5 row_ror:1 row_mask:0xf bank_mask:0xf
	s_nop 0
	v_add_f32_dpp v4, v4, v4 row_bcast:15 row_mask:0xa bank_mask:0xf
	v_add_f32_dpp v5, v5, v5 row_bcast:15 row_mask:0xa bank_mask:0xf
	s_nop 0
	v_add_f32_dpp v4, v4, v4 row_bcast:31 row_mask:0xc bank_mask:0xf
	v_add_f32_dpp v5, v5, v5 row_bcast:31 row_mask:0xc bank_mask:0xf
	s_nop 0
	s_mov_b64 s[0:1], exec
	s_mov_b32 exec_lo, 0
	s_mov_b32 exec_hi, 0x80000000
	s_nop 0
	v_pk_mul_f32 v[4:5], v[4:5], s[20:21] op_sel_hi:[1,0]
	s_nop 0
	v_fma_f32 v4, -v5, v5, v4
	v_max_f32_e32 v4, 0, v4
	v_add_f32_e32 v4, 0x358637bd, v4
	v_mul_f32_e32 v6, 0x4b800000, v4
	v_cmp_gt_f32_e32 vcc, s36, v4
	s_nop 1
	v_cndmask_b32_e32 v4, v4, v6, vcc
	v_rsq_f32_e32 v4, v4
	s_nop 0
	v_mul_f32_e32 v6, 0x45800000, v4
	v_cndmask_b32_e32 v7, v4, v6, vcc
	v_mov_b32_e32 v6, v5
	ds_write_b64 v222, v[6:7] offset:48
.LBB0_309:
	s_or_b64 exec, exec, s[0:1]
	s_waitcnt vmcnt(1)
	v_and_b32_e32 v5, 0xffff0000, v8
	s_waitcnt lgkmcnt(1)
	v_and_b32_e32 v7, 0xffff0000, v9
	v_lshlrev_b32_e32 v9, 16, v9
	v_lshlrev_b32_e32 v8, 16, v8
	v_mul_f32_e32 v16, v8, v8
	v_mov_b32_e32 v4, v9
	v_mov_b32_e32 v17, v9
	s_waitcnt lgkmcnt(0)
	v_mul_f32_e32 v6, v5, v5
	v_mul_f32_e32 v136, v7, v7
	v_pk_add_f32 v[6:7], v[16:17], v[6:7]
	v_pk_mul_f32 v[16:17], v[8:9], v[4:5] op_sel:[1,0] op_sel_hi:[0,1]
	v_pk_add_f32 v[4:5], v[8:9], v[4:5] op_sel:[1,0] op_sel_hi:[0,1]
	v_lshlrev_b32_e32 v13, 16, v10
	v_and_b32_e32 v15, 0xffff0000, v10
	v_mov_b32_e32 v17, v5
	v_mul_f32_e32 v12, v13, v13
	v_mul_f32_e32 v14, v15, v15
	v_pk_add_f32 v[4:5], v[16:17], v[136:137]
	v_and_b32_e32 v9, 0xffff0000, v11
	v_pk_add_f32 v[4:5], v[6:7], v[4:5]
	v_pk_add_f32 v[6:7], v[12:13], v[14:15]
	v_mul_f32_e32 v8, v9, v9
	v_pk_add_f32 v[4:5], v[6:7], v[4:5]
	v_lshlrev_b32_e32 v7, 16, v11
	v_mul_f32_e32 v6, v7, v7
	v_pk_add_f32 v[6:7], v[6:7], v[8:9]
	s_waitcnt vmcnt(0)
	v_lshlrev_b32_e32 v9, 16, v0
	v_and_b32_e32 v11, 0xffff0000, v0
	v_mul_f32_e32 v8, v9, v9
	v_mul_f32_e32 v10, v11, v11
	v_lshlrev_b32_e32 v13, 16, v1
	v_and_b32_e32 v1, 0xffff0000, v1
	v_mul_f32_e32 v12, v13, v13
	v_mul_f32_e32 v0, v1, v1
	v_lshlrev_b32_e32 v15, 16, v2
	v_and_b32_e32 v17, 0xffff0000, v2
	v_pk_add_f32 v[4:5], v[6:7], v[4:5]
	v_pk_add_f32 v[6:7], v[8:9], v[10:11]
	v_mul_f32_e32 v14, v15, v15
	v_mul_f32_e32 v16, v17, v17
	v_lshlrev_b32_e32 v19, 16, v3
	v_and_b32_e32 v3, 0xffff0000, v3
	v_pk_add_f32 v[4:5], v[6:7], v[4:5]
	v_pk_add_f32 v[0:1], v[12:13], v[0:1]
	v_mul_f32_e32 v18, v19, v19
	v_mul_f32_e32 v2, v3, v3
	v_pk_add_f32 v[0:1], v[0:1], v[4:5]
	v_pk_add_f32 v[4:5], v[14:15], v[16:17]
	v_pk_add_f32 v[2:3], v[18:19], v[2:3]
	v_pk_add_f32 v[0:1], v[4:5], v[0:1]
	s_nop 0
	v_pk_add_f32 v[0:1], v[2:3], v[0:1]
	s_nop 1
	v_add_f32_dpp v0, v0, v0 row_ror:8 row_mask:0xf bank_mask:0xf
	v_add_f32_dpp v1, v1, v1 row_ror:8 row_mask:0xf bank_mask:0xf
	s_nop 0
	v_add_f32_dpp v0, v0, v0 row_ror:4 row_mask:0xf bank_mask:0xf
	v_add_f32_dpp v1, v1, v1 row_ror:4 row_mask:0xf bank_mask:0xf
	s_nop 0
	v_add_f32_dpp v0, v0, v0 row_ror:2 row_mask:0xf bank_mask:0xf
	v_add_f32_dpp v1, v1, v1 row_ror:2 row_mask:0xf bank_mask:0xf
	s_nop 0
	v_add_f32_dpp v0, v0, v0 row_ror:1 row_mask:0xf bank_mask:0xf
	v_add_f32_dpp v1, v1, v1 row_ror:1 row_mask:0xf bank_mask:0xf
	s_nop 0
	v_add_f32_dpp v0, v0, v0 row_bcast:15 row_mask:0xa bank_mask:0xf
	v_add_f32_dpp v1, v1, v1 row_bcast:15 row_mask:0xa bank_mask:0xf
	s_nop 0
	v_add_f32_dpp v0, v0, v0 row_bcast:31 row_mask:0xc bank_mask:0xf
	v_add_f32_dpp v1, v1, v1 row_bcast:31 row_mask:0xc bank_mask:0xf
	s_nop 0
	s_mov_b64 s[0:1], exec
	s_mov_b32 exec_lo, 0
	s_mov_b32 exec_hi, 0x80000000
	s_nop 0
	v_pk_mul_f32 v[0:1], v[0:1], s[20:21] op_sel_hi:[1,0]
	s_nop 0
	v_fma_f32 v0, -v1, v1, v0
	v_max_f32_e32 v0, 0, v0
	v_add_f32_e32 v0, 0x358637bd, v0
	v_mul_f32_e32 v2, 0x4b800000, v0
	v_cmp_gt_f32_e32 vcc, s36, v0
	s_nop 1
	v_cndmask_b32_e32 v0, v0, v2, vcc
	v_rsq_f32_e32 v0, v0
	s_nop 0
	v_mul_f32_e32 v2, 0x45800000, v0
	v_cndmask_b32_e32 v3, v0, v2, vcc
	v_mov_b32_e32 v2, v1
	ds_write_b64 v222, v[2:3] offset:56
	s_branch .LBB0_294
